# retention state outputs: eight dependent dword load-wait-store steps per thread replaced by two 16-byte loads, one wait and two 16-byte stores (same fmac operands)
# speedup vs baseline: 1.0068x; 1.0011x over previous
.LBB0_650:
	s_waitcnt vmcnt(0)
	v_lshlrev_b32_e32 v40, 3, v111
	v_bitop3_b32 v40, v40, v102, 24 bitop3:0x6c
	v_lshlrev_b32_e32 v40, 1, v40
	v_mul_u32_u24_e32 v42, 0x480, v112
	v_cvt_pk_bf16_f32 v41, v36, s0
	v_add3_u32 v40, 0, v40, v42
	ds_write_b16 v40, v41 offset:54272
	v_cvt_pk_bf16_f32 v41, v28, s0
	ds_write_b16 v40, v41 offset:63488
	v_cvt_pk_bf16_f32 v41, v37, s0
	ds_write_b16 v40, v41 offset:54416
	v_cvt_pk_bf16_f32 v41, v29, s0
	ds_write_b16 v40, v41 offset:63632
	v_cvt_pk_bf16_f32 v41, v38, s0
	ds_write_b16 v40, v41 offset:54560
	v_cvt_pk_bf16_f32 v41, v30, s0
	ds_write_b16 v40, v41 offset:63776
	v_cvt_pk_bf16_f32 v41, v39, s0
	ds_write_b16 v40, v41 offset:54704
	v_cvt_pk_bf16_f32 v41, v31, s0
	ds_write_b16 v40, v41 offset:63920
	v_cvt_pk_bf16_f32 v41, v32, s0
	ds_write_b16 v40, v41 offset:54848
	v_cvt_pk_bf16_f32 v41, v24, s0
	ds_write_b16 v40, v41 offset:64064
	v_cvt_pk_bf16_f32 v41, v33, s0
	ds_write_b16 v40, v41 offset:54992
	v_cvt_pk_bf16_f32 v41, v25, s0
	ds_write_b16 v40, v41 offset:64208
	v_cvt_pk_bf16_f32 v41, v34, s0
	ds_write_b16 v40, v41 offset:55136
	v_cvt_pk_bf16_f32 v41, v26, s0
	s_cmp_lg_u32 s12, s58
	ds_write_b16 v40, v41 offset:64352
	v_cvt_pk_bf16_f32 v41, v35, s0
	s_cselect_b64 s[58:59], -1, 0
	s_xor_b64 s[60:61], s[54:55], -1
	ds_write_b16 v40, v41 offset:55280
	v_cvt_pk_bf16_f32 v41, v27, s0
	s_or_b64 s[58:59], s[60:61], s[58:59]
	ds_write_b16 v40, v41 offset:64496
	s_and_b64 vcc, exec, s[58:59]
	v_lshlrev_b64 v[40:41], 2, v[104:105]
	v_lshlrev_b32_e32 v42, 5, v112
	s_cbranch_vccnz .LBB0_652
	v_mov_b32_e32 v43, v97
	v_lshl_add_u64 v[44:45], v[42:43], 0, v[40:41]
	v_lshl_add_u64 v[44:45], s[8:9], 0, v[44:45]
	global_load_dwordx4 v[244:247], v[44:45], off
	global_load_dwordx4 v[248:251], v[44:45], off offset:16
	s_and_b32 s58, s81, -5
	s_ashr_i32 s59, s58, 31
	s_lshl_b64 s[58:59], s[58:59], 14
	s_add_u32 s58, s15, s58
	s_addc_u32 s59, s64, s59
	v_lshl_add_u64 v[46:47], s[58:59], 0, v[40:41]
	v_lshl_add_u64 v[46:47], v[46:47], 0, v[96:97]
	s_waitcnt vmcnt(0)
	v_fmac_f32_e32 v244, v106, v36
	v_fmac_f32_e32 v245, v106, v37
	v_fmac_f32_e32 v246, v106, v38
	v_fmac_f32_e32 v247, v106, v39
	v_fmac_f32_e32 v248, v106, v32
	v_fmac_f32_e32 v249, v106, v33
	v_fmac_f32_e32 v250, v106, v34
	v_fmac_f32_e32 v251, v106, v35
	global_store_dwordx4 v[46:47], v[244:247], off
	global_store_dwordx4 v[46:47], v[248:251], off offset:16
	s_nop 1
.LBB0_652:
	s_and_b64 s[54:55], s[54:55], s[56:57]
	s_andn2_b64 vcc, exec, s[54:55]
	s_lshl_b32 s12, s52, 6
	s_cbranch_vccnz .LBB0_601
	s_and_b32 s52, s81, -5
	s_ashr_i32 s53, s52, 31
	s_lshl_b64 s[52:53], s[52:53], 14
	v_mov_b32_e32 v43, v97
	s_add_u32 s52, s33, s52
	v_lshl_add_u64 v[32:33], v[42:43], 0, v[40:41]
	s_addc_u32 s53, s76, s53
	v_lshl_add_u64 v[32:33], s[8:9], 0, v[32:33]
	v_lshl_add_u64 v[34:35], s[52:53], 0, v[40:41]
	s_movk_i32 s52, 0x4000
	v_add_co_u32_e32 v32, vcc, s52, v32
	v_lshl_add_u64 v[34:35], v[34:35], 0, v[96:97]
	s_nop 0
	v_addc_co_u32_e32 v33, vcc, 0, v33, vcc
	global_load_dwordx4 v[244:247], v[32:33], off
	global_load_dwordx4 v[248:251], v[32:33], off offset:16
	s_waitcnt vmcnt(0)
	v_fmac_f32_e32 v244, v108, v28
	v_fmac_f32_e32 v245, v108, v29
	v_fmac_f32_e32 v246, v108, v30
	v_fmac_f32_e32 v247, v108, v31
	v_fmac_f32_e32 v248, v108, v24
	v_fmac_f32_e32 v249, v108, v25
	v_fmac_f32_e32 v250, v108, v26
	v_fmac_f32_e32 v251, v108, v27
	global_store_dwordx4 v[34:35], v[244:247], off
	global_store_dwordx4 v[34:35], v[248:251], off offset:16
	s_nop 1
	s_branch .LBB0_601

.LBB0_1578:
	s_waitcnt vmcnt(0)
	v_lshlrev_b32_e32 v40, 3, v111
	v_bitop3_b32 v40, v40, v102, 24 bitop3:0x6c
	v_lshlrev_b32_e32 v40, 1, v40
	v_mul_u32_u24_e32 v42, 0x480, v112
	v_cvt_pk_bf16_f32 v41, v36, s0
	v_add3_u32 v40, 0, v40, v42
	ds_write_b16 v40, v41 offset:54272
	v_cvt_pk_bf16_f32 v41, v28, s0
	ds_write_b16 v40, v41 offset:63488
	v_cvt_pk_bf16_f32 v41, v37, s0
	ds_write_b16 v40, v41 offset:54416
	v_cvt_pk_bf16_f32 v41, v29, s0
	ds_write_b16 v40, v41 offset:63632
	v_cvt_pk_bf16_f32 v41, v38, s0
	ds_write_b16 v40, v41 offset:54560
	v_cvt_pk_bf16_f32 v41, v30, s0
	ds_write_b16 v40, v41 offset:63776
	v_cvt_pk_bf16_f32 v41, v39, s0
	ds_write_b16 v40, v41 offset:54704
	v_cvt_pk_bf16_f32 v41, v31, s0
	ds_write_b16 v40, v41 offset:63920
	v_cvt_pk_bf16_f32 v41, v32, s0
	ds_write_b16 v40, v41 offset:54848
	v_cvt_pk_bf16_f32 v41, v24, s0
	ds_write_b16 v40, v41 offset:64064
	v_cvt_pk_bf16_f32 v41, v33, s0
	ds_write_b16 v40, v41 offset:54992
	v_cvt_pk_bf16_f32 v41, v25, s0
	ds_write_b16 v40, v41 offset:64208
	v_cvt_pk_bf16_f32 v41, v34, s0
	ds_write_b16 v40, v41 offset:55136
	v_cvt_pk_bf16_f32 v41, v26, s0
	s_cmp_lg_u32 s4, s16
	ds_write_b16 v40, v41 offset:64352
	v_cvt_pk_bf16_f32 v41, v35, s0
	s_cselect_b64 s[4:5], -1, 0
	s_xor_b64 s[48:49], s[44:45], -1
	ds_write_b16 v40, v41 offset:55280
	v_cvt_pk_bf16_f32 v41, v27, s0
	s_or_b64 s[4:5], s[48:49], s[4:5]
	ds_write_b16 v40, v41 offset:64496
	s_and_b64 vcc, exec, s[4:5]
	v_lshlrev_b64 v[40:41], 2, v[104:105]
	v_lshlrev_b32_e32 v42, 5, v112
	s_cbranch_vccnz .LBB0_1580
	v_mov_b32_e32 v43, v97
	v_lshl_add_u64 v[44:45], v[42:43], 0, v[40:41]
	v_lshl_add_u64 v[44:45], s[12:13], 0, v[44:45]
	global_load_dwordx4 v[244:247], v[44:45], off
	global_load_dwordx4 v[248:251], v[44:45], off offset:16
	s_or_b32 s4, s65, 4
	s_ashr_i32 s5, s4, 31
	s_lshl_b64 s[4:5], s[4:5], 14
	s_add_u32 s4, s0, s4
	s_addc_u32 s5, s1, s5
	v_lshl_add_u64 v[46:47], s[4:5], 0, v[40:41]
	v_lshl_add_u64 v[46:47], v[46:47], 0, v[96:97]
	s_waitcnt vmcnt(0)
	v_fmac_f32_e32 v244, v106, v36
	v_fmac_f32_e32 v245, v106, v37
	v_fmac_f32_e32 v246, v106, v38
	v_fmac_f32_e32 v247, v106, v39
	v_fmac_f32_e32 v248, v106, v32
	v_fmac_f32_e32 v249, v106, v33
	v_fmac_f32_e32 v250, v106, v34
	v_fmac_f32_e32 v251, v106, v35
	global_store_dwordx4 v[46:47], v[244:247], off
	global_store_dwordx4 v[46:47], v[248:251], off offset:16
	s_nop 1
.LBB0_1580:
	s_and_b64 s[4:5], s[44:45], s[46:47]
	s_andn2_b64 vcc, exec, s[4:5]
	s_lshl_b32 s4, s66, 6
	s_cbranch_vccnz .LBB0_1529
	v_mov_b32_e32 v43, v97
	v_lshl_add_u64 v[32:33], v[42:43], 0, v[40:41]
	v_lshl_add_u64 v[32:33], s[12:13], 0, v[32:33]
	s_movk_i32 s5, 0x4000
	v_add_co_u32_e32 v32, vcc, s5, v32
	s_or_b32 s44, s65, 4
	s_nop 0
	v_addc_co_u32_e32 v33, vcc, 0, v33, vcc
	global_load_dwordx4 v[244:247], v[32:33], off
	global_load_dwordx4 v[248:251], v[32:33], off offset:16
	s_ashr_i32 s45, s44, 31
	s_lshl_b64 s[44:45], s[44:45], 14
	s_add_u32 s44, s20, s44
	s_addc_u32 s45, s21, s45
	v_lshl_add_u64 v[34:35], s[44:45], 0, v[40:41]
	v_lshl_add_u64 v[34:35], v[34:35], 0, v[96:97]
	s_waitcnt vmcnt(0)
	v_fmac_f32_e32 v244, v108, v28
	v_fmac_f32_e32 v245, v108, v29
	v_fmac_f32_e32 v246, v108, v30
	v_fmac_f32_e32 v247, v108, v31
	v_fmac_f32_e32 v248, v108, v24
	v_fmac_f32_e32 v249, v108, v25
	v_fmac_f32_e32 v250, v108, v26
	v_fmac_f32_e32 v251, v108, v27
	global_store_dwordx4 v[34:35], v[244:247], off
	global_store_dwordx4 v[34:35], v[248:251], off offset:16
	s_nop 1
	s_branch .LBB0_1529
